# baseline (speedup 1.0000x reference)
; #define WAIT_V(n) asm volatile("s_waitcnt vmcnt(%0)" ::"n"(n) : "memory")
;     ...
;     for (int t = 0; t < nt; ++t) {
;       const int cur = t & 1;
;       const char* sa = shm + cur * STAGE_B;
;       const char* sn = shm + (cur ^ 1) * STAGE_B;
;       const bool more = (t + 1 < nt) || (nitem < ntiles);
; #pragma unroll
;       for (int ks = 0; ks < 2; ++ks) {
; #pragma unroll
;         for (int p = 0; p < NP; ++p) {
;           const int q = ks * NP + p;
;           acc[p * 2][0] = __builtin_amdgcn_mfma_f32_16x16x32_bf16(Bq[BDBL ? ks : 0][0], Aq[q & 1][0], acc[p * 2][0], 0, 0, 0);
;           __builtin_amdgcn_sched_barrier(0);
;           if (q == 2 * NP - 1) {
;             WAIT_V(0);
;             __syncthreads();
;             if (more) {
;               if constexpr (BDBL) {
; #pragma unroll
;                 for (int n = 0; n < 4; ++n) Bq[0][n] = *(const bf16x8*)(sn + boff + (n * 2 + 0) * 1024);
;               }
; #pragma unroll
;               for (int i = 0; i < 2; ++i) Aq[0][i] = *(const bf16x8*)(sn + aoff + (i * 2 + 0) * 1024);
;             }
;           } else if (p + 1 < NP) {
; #pragma unroll
;             for (int i = 0; i < 2; ++i) Aq[(q + 1) & 1][i] = *(const bf16x8*)(sa + aoff + (((p + 1) * 2 + i) * 2 + ks) * 1024);
;           } else {
;             if constexpr (BDBL) {
; #pragma unroll
;               for (int n = 0; n < 4; ++n) Bq[1][n] = *(const bf16x8*)(sa + boff + (n * 2 + 1) * 1024);
;             }
; #pragma unroll
;             for (int i = 0; i < 2; ++i) Aq[(q + 1) & 1][i] = *(const bf16x8*)(sa + aoff + (i * 2 + 1) * 1024);
;           }
;           __builtin_amdgcn_sched_barrier(0);
; #pragma unroll
;           for (int i = 0; i < 2; ++i)
; #pragma unroll
;             for (int n = 0; n < 4; ++n)
;               if (i + n > 0)
;                 acc[p * 2 + i][n] = __builtin_amdgcn_mfma_f32_16x16x32_bf16(Bq[BDBL ? ks : 0][n], Aq[q & 1][i], acc[p * 2 + i][n], 0, 0, 0);
;           __builtin_amdgcn_sched_barrier(0);
;           if (q == GLDS_AT) {
;             if (t + 1 < nt) GLDS_STAGE(cur ^ 1, t + 1, Ab, Bb);
;             else if (nitem < ntiles) GLDS_STAGE(0, 0, nAb, nBb);
;             __builtin_amdgcn_sched_barrier(0);
.LBB0_1081:
	s_waitcnt lgkmcnt(0)
	v_mfma_f32_16x16x32_bf16 v[84:87], v[12:15], v[20:23], v[84:87]
	s_and_b32 s7, s88, 1
	s_add_i32 s88, s88, 1
	s_mul_i32 s20, s7, 0xc000
	s_cmp_lt_u32 s88, s95
	s_cselect_b64 s[18:19], -1, 0
	v_add_u32_e32 v100, s20, v129
	v_add_u32_e32 v104, s20, v128
	ds_read_b128 v[106:109], v104 offset:4096
	ds_read_b128 v[132:135], v104 offset:6144
	v_mfma_f32_16x16x32_bf16 v[68:71], v[8:11], v[20:23], v[68:71]
	v_mfma_f32_16x16x32_bf16 v[52:55], v[4:7], v[20:23], v[52:55]
	v_mfma_f32_16x16x32_bf16 v[36:39], v[0:3], v[20:23], v[36:39]
	s_mov_b64 s[20:21], -1
	s_and_b64 vcc, exec, s[18:19]
	s_cbranch_vccnz .LBB0_1085
	s_andn2_b64 vcc, exec, s[4:5]
	s_cbranch_vccnz .LBB0_1084
	s_mov_b32 m0, s22
	s_nop 0
	global_load_lds_dwordx4 v[112:113], off
	s_add_i32 m0, s22, 0x2000
	s_nop 0
	global_load_lds_dwordx4 v[120:121], off
	s_add_i32 m0, s22, 0x4000
	s_nop 0
	global_load_lds_dwordx4 v[114:115], off
	s_add_i32 m0, s22, 0x6000
	s_nop 0
	global_load_lds_dwordx4 v[122:123], off
	s_add_i32 m0, s22, 0x8000
	s_nop 0
	global_load_lds_dwordx4 v[124:125], off
	s_add_i32 m0, s22, 0xa000
	s_nop 0
	global_load_lds_dwordx4 v[126:127], off

;     ...
;                 acc[p * 2 + i][n] = __builtin_amdgcn_mfma_f32_16x16x32_bf16(Bq[BDBL ? ks : 0][n], Aq[q & 1][i], acc[p * 2 + i][n], 0, 0, 0);
;           __builtin_amdgcn_sched_barrier(0);
;           if (q == GLDS_AT) {
;             if (t + 1 < nt) GLDS_STAGE(cur ^ 1, t + 1, Ab, Bb);
;             else if (nitem < ntiles) GLDS_STAGE(0, 0, nAb, nBb);
;             __builtin_amdgcn_sched_barrier(0);
;           }
.LBB0_1085:
	s_xor_b32 s7, s7, 1
	s_andn2_b64 vcc, exec, s[20:21]
	s_mul_i32 s20, s7, 0xc000
	s_cbranch_vccnz .Lmy_o128j
	s_add_i32 s21, s20, s22
	s_add_i32 s74, s6, 0xfffa0000
	v_lshl_add_u64 v[168:169], v[116:117], 0, s[74:75]
	s_mov_b32 m0, s21
	s_add_i32 s58, s6, 0xfffc0000
	s_mov_b32 s59, s75
	s_add_i32 s7, s21, 0x4000
	global_load_lds_dwordx4 v[168:169], off
	v_lshl_add_u64 v[168:169], v[116:117], 0, s[58:59]
	s_add_i32 m0, s21, 0x2000
	v_lshl_add_u64 v[170:171], v[118:119], 0, s[58:59]
	global_load_lds_dwordx4 v[168:169], off
	v_lshl_add_u64 v[168:169], v[118:119], 0, s[74:75]
	s_mov_b32 m0, s7
	s_mov_b32 s7, s75
	global_load_lds_dwordx4 v[168:169], off
	s_add_i32 m0, s21, 0x6000
	v_lshl_add_u64 v[168:169], v[168:169], 0, s[96:97]
	global_load_lds_dwordx4 v[170:171], off
	s_add_i32 m0, s21, 0x8000
	s_nop 0
	global_load_lds_dwordx4 v[168:169], off
	v_lshl_add_u64 v[168:169], v[118:119], 0, s[6:7]
	s_add_i32 m0, s21, 0xa000
	s_nop 0
	global_load_lds_dwordx4 v[168:169], off
.Lmy_o128j:
	v_mfma_f32_16x16x32_bf16 v[80:83], v[12:15], v[16:19], v[80:83]
	v_mfma_f32_16x16x32_bf16 v[64:67], v[8:11], v[16:19], v[64:67]
	v_mfma_f32_16x16x32_bf16 v[48:51], v[4:7], v[16:19], v[48:51]
	v_mfma_f32_16x16x32_bf16 v[32:35], v[0:3], v[16:19], v[32:35]
	s_waitcnt lgkmcnt(1)
	v_mfma_f32_16x16x32_bf16 v[76:79], v[12:15], v[106:109], v[76:79]
	ds_read_b128 v[88:91], v100 offset:17408
	ds_read_b128 v[92:95], v100 offset:19456
	ds_read_b128 v[96:99], v100 offset:21504
	ds_read_b128 v[100:103], v100 offset:23552
	ds_read_b128 v[20:23], v104 offset:1024
	ds_read_b128 v[16:19], v104 offset:3072
	v_mfma_f32_16x16x32_bf16 v[60:63], v[8:11], v[106:109], v[60:63]
	v_mfma_f32_16x16x32_bf16 v[44:47], v[4:7], v[106:109], v[44:47]
	v_mfma_f32_16x16x32_bf16 v[28:31], v[0:3], v[106:109], v[28:31]
	s_waitcnt lgkmcnt(6)
	v_mfma_f32_16x16x32_bf16 v[72:75], v[12:15], v[132:135], v[72:75]
	v_mfma_f32_16x16x32_bf16 v[56:59], v[8:11], v[132:135], v[56:59]
	v_mfma_f32_16x16x32_bf16 v[40:43], v[4:7], v[132:135], v[40:43]
	v_mfma_f32_16x16x32_bf16 v[24:27], v[0:3], v[132:135], v[24:27]
